# as v131 but the P4a->P4b panel counter read is issued right after the own-tile staging DMAs (newest outstanding op) and checked before the K-loop; same size and byte phases
# baseline (speedup 1.0000x reference)
.LBB0_946:
	s_mov_b64 s[2:3], s[74:75]
	s_waitcnt vmcnt(0)
	s_barrier
	s_getreg_b32 s4, hwreg(HW_REG_HW_ID, 0, 6)
	s_lshl_b32 s4, s4, 2
	s_and_b32 s4, s4, 0xfc
	s_add_i32 s4, s4, 0
	s_add_i32 s4, s4, 0x20200
	s_waitcnt vmcnt(0)
	v_mov_b32_e32 v0, s4
	ds_read_b32 v0, v0
	v_mbcnt_lo_u32_b32 v1, -1, 0
	v_mbcnt_hi_u32_b32 v1, -1, v1
	s_waitcnt lgkmcnt(0)
	v_readfirstlane_b32 s4, v0
	s_lshl_b32 s4, s4, 6
	v_sub_u32_e32 v0, 0, v1
	v_cmp_eq_u32_e32 vcc, s4, v0
	s_and_saveexec_b64 s[4:5], vcc
	s_cbranch_execz .LBB0_949
	s_mov_b64 s[8:9], exec
	v_mbcnt_lo_u32_b32 v0, s8, 0
	v_mbcnt_hi_u32_b32 v0, s9, v0
	v_cmp_eq_u32_e32 vcc, 0, v0
	s_and_b64 s[10:11], exec, vcc
	s_mov_b64 exec, s[10:11]
	s_cbranch_execz .LBB0_949
	s_load_dwordx2 s[2:3], s[2:3], 0xf8
	s_lshl_b64 s[10:11], s[0:1], 2
	v_mov_b32_e32 v1, 0xc000
	s_waitcnt lgkmcnt(0)
	s_add_u32 s2, s2, s10
	s_addc_u32 s3, s3, s11
	s_bcnt1_i32_b64 s8, s[8:9]
	v_mov_b32_e32 v0, s8
	global_atomic_add v1, v0, s[2:3] offset:2048
.LBB0_949:
	s_or_b64 exec, exec, s[4:5]
	s_mov_b64 s[4:5], s[74:75]
	s_getreg_b32 s2, hwreg(HW_REG_HW_ID, 0, 6)
	s_lshl_b32 s2, s2, 2
	s_and_b32 s2, s2, 0xfc
	s_add_i32 s2, s2, 0
	s_add_i32 s2, s2, 0x20200
	v_mov_b32_e32 v0, s2
	ds_read_b32 v0, v0
	v_mbcnt_lo_u32_b32 v1, -1, 0
	v_mbcnt_hi_u32_b32 v1, -1, v1
	s_waitcnt lgkmcnt(0)
	v_readfirstlane_b32 s2, v0
	s_lshl_b32 s2, s2, 6
	v_sub_u32_e32 v0, 0, v1
	v_cmp_eq_u32_e32 vcc, s2, v0
	s_and_saveexec_b64 s[2:3], vcc
	s_branch .LBB0_962
	s_nop 0
.LBB0_962:
	s_or_b64 exec, exec, s[2:3]
	s_mov_b64 s[2:3], s[74:75]
	s_mov_b64 s[8:9], s[74:75]
	s_mov_b64 s[0:1], s[74:75]
	s_mov_b64 s[12:13], s[74:75]
	s_barrier
	s_getreg_b32 s4, hwreg(HW_REG_HW_ID, 0, 6)
	s_lshl_b32 s4, s4, 2
	s_and_b32 s4, s4, 0xfc
	s_add_i32 s4, s4, 0
	s_add_i32 s4, s4, 0x20200
	v_mov_b32_e32 v0, s4
	ds_read_b32 v0, v0
	v_mbcnt_lo_u32_b32 v56, -1, 0
	v_mbcnt_hi_u32_b32 v56, -1, v56
	s_and_b64 vcc, exec, s[6:7]
	s_waitcnt lgkmcnt(0)
	v_readfirstlane_b32 s4, v0
	s_nop 1
	v_lshl_add_u32 v30, s4, 6, v56
	s_nop 0
	v_readfirstlane_b32 s17, v30
	s_cbranch_vccnz .LBB0_1074
	s_load_dwordx2 s[4:5], s[2:3], 0xf8
	s_nop 0
	s_load_dwordx2 s[2:3], s[8:9], 0xf8
	s_nop 0
	s_load_dwordx4 s[8:11], s[12:13], 0xf0
	s_getreg_b32 s6, hwreg(HW_REG_HW_ID, 0, 6)
	s_lshl_b32 s6, s6, 2
	s_and_b32 s6, s6, 0xfc
	s_add_i32 s6, s6, 0
	s_add_i32 s6, s6, 0x20200
	v_mov_b32_e32 v0, s6
	s_ashr_i32 s20, s17, 8
	ds_read_b32 v0, v0
	s_lshl_b32 s16, s20, 6
	v_readlane_b32 s12, v253, 61
	v_mbcnt_lo_u32_b32 v4, -1, 0
	v_mbcnt_hi_u32_b32 v4, -1, v4
	v_readlane_b32 s6, v253, 9
	s_waitcnt lgkmcnt(0)
	v_and_or_b32 v0, v4, 15, s16
	v_readlane_b32 s13, v253, 62
	v_add_u32_e32 v24, s6, v0
	s_mov_b64 s[6:7], -1
	s_and_b64 vcc, exec, s[12:13]
	s_cbranch_vccz .LBB0_965
	v_ashrrev_i32_e32 v25, 31, v24
	s_mov_b64 s[6:7], 0
	v_mov_b64_e32 v[0:1], v[24:25]

.LBB0_1029:
	v_and_b32_e32 v142, 15, v56
	v_bfe_u32 v143, v56, 4, 2
	v_or_b32_e32 v63, s16, v142
	v_lshlrev_b32_e32 v80, 4, v143
	v_lshlrev_b32_e32 v81, 6, v63
	s_movk_i32 s26, 0x3c0
	v_lshlrev_b32_e32 v63, 2, v63
	v_and_or_b32 v81, v81, s26, v80
	s_lshl_b32 s20, s20, 13
	v_and_b32_e32 v63, 32, v63
	v_lshlrev_b32_e32 v56, 2, v56
	v_bitop3_b32 v63, v81, s20, v63 bitop3:0xde
	v_lshl_or_b32 v80, v142, 6, v80
	s_lshl_b32 s20, s19, 12
	v_and_b32_e32 v56, 32, v56
	s_add_i32 m0, s22, 0x18000
	v_lshl_add_u64 v[30:31], v[30:31], 0, s[88:89]
	v_bitop3_b32 v144, v80, s20, v56 bitop3:0xde
	s_waitcnt vmcnt(2)
	s_barrier
	global_load_lds_dwordx4 v[30:31], off
	v_lshl_add_u64 v[28:29], v[28:29], 0, s[88:89]
	s_add_i32 m0, s22, 0x1a000
	s_add_i32 s20, s22, 0x8000
	global_load_lds_dwordx4 v[28:29], off
	v_lshl_add_u64 v[26:27], v[26:27], 0, s[88:89]
	s_mov_b32 m0, s20
	s_add_i32 s26, s22, 0xa000
	global_load_lds_dwordx4 v[26:27], off
	v_lshl_add_u64 v[24:25], v[24:25], 0, s[88:89]
	s_mov_b32 m0, s26
	v_readlane_b32 s28, v253, 27
	global_load_lds_dwordx4 v[24:25], off
	s_cmp_lg_u32 s22, 0
	s_cbranch_scc1 .Lmy_pw2_i
	s_load_dwordx2 vcc, s[74:75], 0xf8
	s_waitcnt lgkmcnt(0)
	s_add_u32 vcc_lo, vcc_lo, s100
	s_addc_u32 vcc_hi, vcc_hi, 0
	s_add_u32 vcc_lo, vcc_lo, 0x1400
	s_addc_u32 vcc_hi, vcc_hi, 0
	global_load_dword v138, v137, vcc sc1
.Lmy_pw2_i:
	v_lshlrev_b32_e32 v24, 14, v57
	v_readlane_b32 s29, v253, 28
	s_add_u32 s27, s4, s28
	v_and_b32_e32 v24, 0xffff8000, v24
	s_addc_u32 s28, s5, s29
	v_readlane_b32 s29, v253, 26
	v_lshl_add_u32 v24, v58, 11, v24
	v_and_b32_e32 v25, 1, v57
	s_add_u32 s4, s4, s29
	v_readlane_b32 s29, v253, 29
	v_lshl_or_b32 v24, v25, 6, v24
	s_addc_u32 s5, s5, s29
	v_lshl_add_u32 v24, v59, 1, v24
	v_mov_b32_e32 v25, v137
	v_lshl_add_u64 v[134:135], s[4:5], 0, v[24:25]
	v_lshlrev_b32_e32 v24, 14, v60
	v_and_b32_e32 v24, 0xffff8000, v24
	v_lshl_add_u32 v24, v61, 11, v24
	v_and_b32_e32 v25, 1, v60
	v_lshl_or_b32 v24, v25, 6, v24
	v_lshl_add_u32 v24, v62, 1, v24
	v_mov_b32_e32 v25, v137
	v_lshl_add_u64 v[140:141], s[4:5], 0, v[24:25]
	v_readlane_b32 s4, v253, 31
	s_add_u32 s2, s2, s4
	v_readlane_b32 s4, v253, 32
	s_waitcnt vmcnt(4)
	s_addc_u32 s3, s3, s4
	s_add_u32 s14, s2, s14
	v_mov_b32_e32 v80, 0
	s_addc_u32 s15, s3, s15
	s_mov_b32 s29, -2
	s_mov_b64 s[2:3], 0
	s_mov_b32 s2, s101
	v_add_u32_e32 v145, 0, v63
	v_mov_b32_e32 v81, v80
	v_mov_b32_e32 v82, v80
	v_mov_b32_e32 v83, v80
	v_mov_b32_e32 v84, v80
	v_mov_b32_e32 v85, v80
	v_mov_b32_e32 v86, v80
	v_mov_b32_e32 v87, v80
	v_mov_b32_e32 v88, v80
	v_mov_b32_e32 v89, v80
	v_mov_b32_e32 v90, v80
	v_mov_b32_e32 v91, v80
	v_mov_b32_e32 v92, v80
	v_mov_b32_e32 v93, v80
	v_mov_b32_e32 v94, v80
	v_mov_b32_e32 v95, v80
	v_mov_b32_e32 v96, v80
	v_mov_b32_e32 v97, v80
	v_mov_b32_e32 v98, v80
	v_mov_b32_e32 v99, v80
	v_mov_b32_e32 v100, v80
	v_mov_b32_e32 v101, v80
	v_mov_b32_e32 v102, v80
	v_mov_b32_e32 v103, v80
	v_mov_b32_e32 v104, v80
	v_mov_b32_e32 v105, v80
	v_mov_b32_e32 v106, v80
	v_mov_b32_e32 v107, v80
	v_mov_b32_e32 v108, v80
	v_mov_b32_e32 v109, v80
	v_mov_b32_e32 v110, v80
	v_mov_b32_e32 v111, v80
	v_mov_b32_e32 v112, v80
	v_mov_b32_e32 v113, v80
	v_mov_b32_e32 v114, v80
	v_mov_b32_e32 v115, v80
	v_mov_b32_e32 v116, v80
	v_mov_b32_e32 v117, v80
	v_mov_b32_e32 v118, v80
	v_mov_b32_e32 v119, v80
	v_mov_b32_e32 v56, v80
	v_mov_b32_e32 v57, v80
	v_mov_b32_e32 v58, v80
	v_mov_b32_e32 v59, v80
	v_mov_b32_e32 v60, v80
	v_mov_b32_e32 v61, v80
	v_mov_b32_e32 v62, v80
	v_mov_b32_e32 v63, v80
	v_mov_b32_e32 v28, v80
	v_mov_b32_e32 v29, v80
	v_mov_b32_e32 v30, v80
	v_mov_b32_e32 v31, v80
	v_mov_b32_e32 v24, v80
	v_mov_b32_e32 v25, v80
	v_mov_b32_e32 v26, v80
	v_mov_b32_e32 v27, v80
	v_mov_b32_e32 v120, v80
	v_mov_b32_e32 v121, v80
	v_mov_b32_e32 v122, v80
	v_mov_b32_e32 v123, v80
	v_mov_b32_e32 v124, v80
	v_mov_b32_e32 v125, v80
	v_mov_b32_e32 v126, v80
	v_mov_b32_e32 v127, v80
	s_cmp_lg_u32 s22, 0
	s_cbranch_scc1 .Lmy_pw2_done
	s_branch .Lmy_pw2_chk

.Lmy_pw2_chk:
	s_waitcnt vmcnt(0)
	v_cmp_lt_u32_e32 vcc, 7, v138
	s_cbranch_vccnz .Lmy_pw2_ok
	s_sleep 1
	s_branch .Lmy_pw2_poll
